# as DAB + D loops compute the far-tile row-max chain under the P.V MFMAs (near tiles recompute it)
# baseline (speedup 1.0000x reference)
; #define SBAR() __builtin_amdgcn_sched_barrier(0)
; template <int D0> __device__ __forceinline__ void pv_one(f32x16& od, int vb, bf16x8 pa0, bf16x8 pa1, bf16x8 pa2, bf16x8 pa3) {
;     const s16x4 l0 = tr_read<v_rd_off(D0, 0, 0)>(vb), h0 = tr_read<v_rd_off(D0, 0, 1)>(vb), l1 = tr_read<v_rd_off(D0, 1, 0)>(vb), h1 = tr_read<v_rd_off(D0, 1, 1)>(vb);
;     const s16x4 l2 = tr_read<v_rd_off(D0, 2, 0)>(vb), h2 = tr_read<v_rd_off(D0, 2, 1)>(vb), l3 = tr_read<v_rd_off(D0, 3, 0)>(vb), h3 = tr_read<v_rd_off(D0, 3, 1)>(vb);
;     asm volatile("s_waitcnt lgkmcnt(0)" ::: "memory"); SBAR();
;     ...
;     od = __builtin_amdgcn_mfma_f32_32x32x16_bf16(pa0, PK(l0, h0), od, 0, 0, 0);
;     od = __builtin_amdgcn_mfma_f32_32x32x16_bf16(pa1, PK(l1, h1), od, 0, 0, 0);
;     od = __builtin_amdgcn_mfma_f32_32x32x16_bf16(pa2, PK(l2, h2), od, 0, 0, 0);
;     od = __builtin_amdgcn_mfma_f32_32x32x16_bf16(pa3, PK(l3, h3), od, 0, 0, 0);
;     ...
; }
; template <bool RSM> __device__ __forceinline__ void pv_d0(f32x16* o, f32x16& lacc, int vb, bf16x8 pa0, bf16x8 pa1, bf16x8 pa2, bf16x8 pa3) {
;     if (RSM) {
;         const bf16x8 ones = {0x3F80, 0x3F80, 0x3F80, 0x3F80, 0x3F80, 0x3F80, 0x3F80, 0x3F80};
;         lacc = __builtin_amdgcn_mfma_f32_32x32x16_bf16(pa0, ones, lacc, 0, 0, 0);
;         lacc = __builtin_amdgcn_mfma_f32_32x32x16_bf16(pa1, ones, lacc, 0, 0, 0);
;         lacc = __builtin_amdgcn_mfma_f32_32x32x16_bf16(pa2, ones, lacc, 0, 0, 0);
;         lacc = __builtin_amdgcn_mfma_f32_32x32x16_bf16(pa3, ones, lacc, 0, 0, 0); }
;     pv_one<0>(o[0], vb, pa0, pa1, pa2, pa3); pv_one<1>(o[1], vb, pa0, pa1, pa2, pa3); pv_one<2>(o[2], vb, pa0, pa1, pa2, pa3); pv_one<3>(o[3], vb, pa0, pa1, pa2, pa3);
; template <int MODE, bool FIRST, bool FOLD>
; __device__ __forceinline__ bool partialSM(f32x16& p0, f32x16& p1, float& m_reg, float& alpha, int relbase, bool near, const float* lut, float cb) {
;     ...
;     float pmax = p0[0];
; #pragma unroll
;     for (int r = 1; r < 16; ++r) pmax = fmaxf(pmax, p0[r]);
; #pragma unroll
;     for (int r = 0; r < 16; ++r) pmax = fmaxf(pmax, p1[r]);
.LBB0_704:
	s_mov_b32 s38, s36
	s_mov_b32 s39, s36
	s_mov_b32 s37, s36
	v_mov_b64_e32 v[134:135], s[38:39]
	v_mov_b64_e32 v[132:133], s[36:37]
	s_lshl_b32 s23, s35, 14
	v_add_u32_e32 v0, s23, v230
	v_mfma_f32_32x32x16_bf16 v[96:111], v[6:9], v[132:135], v[96:111]
	ds_read_b64_tr_b16 v[136:137], v0 offset:0
	ds_read_b64_tr_b16 v[138:139], v0 offset:0x800
	ds_read_b64_tr_b16 v[140:141], v0 offset:0x1000
	ds_read_b64_tr_b16 v[142:143], v0 offset:0x1800
	ds_read_b64_tr_b16 v[192:193], v0 offset:0x2000
	ds_read_b64_tr_b16 v[194:195], v0 offset:0x2800
	ds_read_b64_tr_b16 v[196:197], v0 offset:0x3000
	v_mfma_f32_32x32x16_bf16 v[96:111], v[2:5], v[132:135], v[96:111]
	ds_read_b64_tr_b16 v[198:199], v0 offset:0x3800
	s_waitcnt lgkmcnt(0)
	v_mfma_f32_32x32x16_bf16 v[96:111], v[128:131], v[132:135], v[96:111]
	v_mfma_f32_32x32x16_bf16 v[96:111], v[10:13], v[132:135], v[96:111]
	v_mfma_f32_32x32x16_bf16 v[80:95], v[6:9], v[136:139], v[80:95]
	v_max_f32_e32 v203, v161, v161
	v_max_f32_e32 v204, v160, v160
	ds_read_b64_tr_b16 v[132:133], v0 offset:0x200
	ds_read_b64_tr_b16 v[134:135], v0 offset:0xa00
	ds_read_b64_tr_b16 v[136:137], v0 offset:0x1200
	ds_read_b64_tr_b16 v[138:139], v0 offset:0x1a00
	v_mfma_f32_32x32x16_bf16 v[80:95], v[2:5], v[140:143], v[80:95]
	v_max_f32_e32 v203, v204, v203
	v_max_f32_e32 v204, v144, v145
	ds_read_b64_tr_b16 v[140:141], v0 offset:0x2200
	ds_read_b64_tr_b16 v[142:143], v0 offset:0x2a00
	v_mfma_f32_32x32x16_bf16 v[80:95], v[128:131], v[192:195], v[80:95]
	v_max3_f32 v203, v203, v162, v163
	ds_read_b64_tr_b16 v[192:193], v0 offset:0x3200
	ds_read_b64_tr_b16 v[194:195], v0 offset:0x3a00
	s_waitcnt lgkmcnt(0)
	v_mfma_f32_32x32x16_bf16 v[80:95], v[10:13], v[196:199], v[80:95]
	v_max3_f32 v204, v204, v146, v147
	v_mfma_f32_32x32x16_bf16 v[64:79], v[6:9], v[132:135], v[64:79]
	v_max3_f32 v203, v203, v164, v165
	ds_read_b64_tr_b16 v[132:133], v0 offset:0x400
	ds_read_b64_tr_b16 v[134:135], v0 offset:0xc00
	v_mfma_f32_32x32x16_bf16 v[64:79], v[2:5], v[136:139], v[64:79]
	v_max3_f32 v204, v204, v148, v149
	ds_read_b64_tr_b16 v[136:137], v0 offset:0x1400
	ds_read_b64_tr_b16 v[138:139], v0 offset:0x1c00
	v_mfma_f32_32x32x16_bf16 v[64:79], v[128:131], v[140:143], v[64:79]
	v_max3_f32 v203, v203, v166, v167
	ds_read_b64_tr_b16 v[140:141], v0 offset:0x2400
	ds_read_b64_tr_b16 v[142:143], v0 offset:0x2c00
	v_mfma_f32_32x32x16_bf16 v[64:79], v[10:13], v[192:195], v[64:79]
	v_max3_f32 v204, v204, v150, v151
	ds_read_b64_tr_b16 v[192:193], v0 offset:0x3400
	ds_read_b64_tr_b16 v[194:195], v0 offset:0x3c00
	s_waitcnt lgkmcnt(0)
	v_mfma_f32_32x32x16_bf16 v[48:63], v[6:9], v[132:135], v[48:63]
	v_max3_f32 v203, v203, v168, v169
	ds_read_b64_tr_b16 v[132:133], v0 offset:0x600
	ds_read_b64_tr_b16 v[134:135], v0 offset:0xe00
	v_mfma_f32_32x32x16_bf16 v[48:63], v[2:5], v[136:139], v[48:63]
	v_max3_f32 v204, v204, v152, v153
	ds_read_b64_tr_b16 v[136:137], v0 offset:0x1600
	ds_read_b64_tr_b16 v[138:139], v0 offset:0x1e00
	v_mfma_f32_32x32x16_bf16 v[48:63], v[128:131], v[140:143], v[48:63]
	v_max3_f32 v203, v203, v170, v171
	ds_read_b64_tr_b16 v[140:141], v0 offset:0x2600
	ds_read_b64_tr_b16 v[142:143], v0 offset:0x2e00
	v_mfma_f32_32x32x16_bf16 v[48:63], v[10:13], v[192:195], v[48:63]
	v_max3_f32 v204, v204, v154, v155
	ds_read_b64_tr_b16 v[192:193], v0 offset:0x3600
	ds_read_b64_tr_b16 v[194:195], v0 offset:0x3e00
	s_waitcnt lgkmcnt(0)
	v_mfma_f32_32x32x16_bf16 v[32:47], v[6:9], v[132:135], v[32:47]
	v_max3_f32 v203, v203, v172, v173
	s_and_b64 vcc, exec, s[0:1]
	v_mfma_f32_32x32x16_bf16 v[32:47], v[2:5], v[136:139], v[32:47]
	v_max3_f32 v204, v204, v156, v157
	v_mfma_f32_32x32x16_bf16 v[32:47], v[128:131], v[140:143], v[32:47]
	v_max3_f32 v203, v203, v174, v175
	v_mfma_f32_32x32x16_bf16 v[32:47], v[10:13], v[192:195], v[32:47]
	v_max3_f32 v204, v204, v158, v159
	s_cbranch_vccnz .LBB0_709

; template <int MODE, bool FIRST, bool FOLD>
; __device__ __forceinline__ bool partialSM(f32x16& p0, f32x16& p1, float& m_reg, float& alpha, int relbase, bool near, const float* lut, float cb) {
;     ...
;     float pmax = p0[0];
; #pragma unroll
;     for (int r = 1; r < 16; ++r) pmax = fmaxf(pmax, p0[r]);
; #pragma unroll
;     for (int r = 0; r < 16; ++r) pmax = fmaxf(pmax, p1[r]);
;     { auto rr = __builtin_amdgcn_permlane32_swap(__float_as_uint(pmax), __float_as_uint(pmax), false, false);
;       pmax = fmaxf(__uint_as_float(rr[0]), __uint_as_float(rr[1])); }
;     bool resc;
;     if (FIRST && MODE != 2) resc = true; else resc = __any(pmax > THR2);
; template <int NQ, int MODE> ...
;     ...
;     f32x16 cinit = f32x16{}; float cur_cb = 0.f; bool dirty = true;
.LBB0_711:
	v_max_f32_e32 v0, v161, v161
	v_max_f32_e32 v10, v160, v160
	v_max_f32_e32 v0, v10, v0
	v_max_f32_e32 v10, v144, v145
	v_max3_f32 v0, v0, v162, v163
	v_max3_f32 v10, v10, v146, v147
	v_max3_f32 v0, v0, v164, v165
	v_max3_f32 v10, v10, v148, v149
	v_max3_f32 v0, v0, v166, v167
	v_max3_f32 v10, v10, v150, v151
	v_max3_f32 v0, v0, v168, v169
	v_max3_f32 v10, v10, v152, v153
	v_max3_f32 v0, v0, v170, v171
	v_max3_f32 v10, v10, v154, v155
	v_max3_f32 v0, v0, v172, v173
	v_max3_f32 v10, v10, v156, v157
	v_max3_f32 v0, v0, v174, v175
	v_max3_f32 v10, v10, v158, v159
	v_max_f32_e32 v0, v0, v10
	s_branch .Lmy_join_0
.Lmy_far_0:
	v_max_f32_e32 v0, v203, v204
.Lmy_join_0:
	v_mov_b32_e32 v10, v0
	s_nop 1
	v_permlane32_swap_b32_e32 v0, v10
	v_max_f32_e32 v10, v0, v10
	v_cmp_lt_f32_e32 vcc, s51, v10
	s_cmp_lg_u64 vcc, 0
	s_cselect_b64 s[22:23], -1, 0
	v_mov_b32_e32 v0, 1.0
	s_cbranch_vccnz .LBB0_731

; #define SBAR() __builtin_amdgcn_sched_barrier(0)
; template <int D0> __device__ __forceinline__ void pv_one(f32x16& od, int vb, bf16x8 pa0, bf16x8 pa1, bf16x8 pa2, bf16x8 pa3) {
;     const s16x4 l0 = tr_read<v_rd_off(D0, 0, 0)>(vb), h0 = tr_read<v_rd_off(D0, 0, 1)>(vb), l1 = tr_read<v_rd_off(D0, 1, 0)>(vb), h1 = tr_read<v_rd_off(D0, 1, 1)>(vb);
;     const s16x4 l2 = tr_read<v_rd_off(D0, 2, 0)>(vb), h2 = tr_read<v_rd_off(D0, 2, 1)>(vb), l3 = tr_read<v_rd_off(D0, 3, 0)>(vb), h3 = tr_read<v_rd_off(D0, 3, 1)>(vb);
;     asm volatile("s_waitcnt lgkmcnt(0)" ::: "memory"); SBAR();
;     ...
;     od = __builtin_amdgcn_mfma_f32_32x32x16_bf16(pa0, PK(l0, h0), od, 0, 0, 0);
;     od = __builtin_amdgcn_mfma_f32_32x32x16_bf16(pa1, PK(l1, h1), od, 0, 0, 0);
;     od = __builtin_amdgcn_mfma_f32_32x32x16_bf16(pa2, PK(l2, h2), od, 0, 0, 0);
;     od = __builtin_amdgcn_mfma_f32_32x32x16_bf16(pa3, PK(l3, h3), od, 0, 0, 0);
;     ...
; }
; template <bool RSM> __device__ __forceinline__ void pv_d0(f32x16* o, f32x16& lacc, int vb, bf16x8 pa0, bf16x8 pa1, bf16x8 pa2, bf16x8 pa3) {
;     if (RSM) {
;         const bf16x8 ones = {0x3F80, 0x3F80, 0x3F80, 0x3F80, 0x3F80, 0x3F80, 0x3F80, 0x3F80};
;         lacc = __builtin_amdgcn_mfma_f32_32x32x16_bf16(pa0, ones, lacc, 0, 0, 0);
;         lacc = __builtin_amdgcn_mfma_f32_32x32x16_bf16(pa1, ones, lacc, 0, 0, 0);
;         lacc = __builtin_amdgcn_mfma_f32_32x32x16_bf16(pa2, ones, lacc, 0, 0, 0);
;         lacc = __builtin_amdgcn_mfma_f32_32x32x16_bf16(pa3, ones, lacc, 0, 0, 0); }
;     pv_one<0>(o[0], vb, pa0, pa1, pa2, pa3); pv_one<1>(o[1], vb, pa0, pa1, pa2, pa3); pv_one<2>(o[2], vb, pa0, pa1, pa2, pa3); pv_one<3>(o[3], vb, pa0, pa1, pa2, pa3);
; template <int MODE, bool FIRST, bool FOLD>
; __device__ __forceinline__ bool partialSM(f32x16& p0, f32x16& p1, float& m_reg, float& alpha, int relbase, bool near, const float* lut, float cb) {
;     ...
;     float pmax = p0[0];
; #pragma unroll
;     for (int r = 1; r < 16; ++r) pmax = fmaxf(pmax, p0[r]);
; #pragma unroll
;     for (int r = 0; r < 16; ++r) pmax = fmaxf(pmax, p1[r]);
.LBB0_719:
	s_mov_b32 s38, s36
	s_mov_b32 s39, s36
	s_mov_b32 s37, s36
	v_mov_b64_e32 v[150:151], s[38:39]
	v_mov_b64_e32 v[148:149], s[36:37]
	s_lshl_b32 s37, s35, 14
	v_add_u32_e32 v14, s37, v230
	v_mfma_f32_32x32x16_bf16 v[96:111], v[6:9], v[148:151], v[96:111]
	ds_read_b64_tr_b16 v[152:153], v14 offset:0
	ds_read_b64_tr_b16 v[154:155], v14 offset:0x800
	ds_read_b64_tr_b16 v[156:157], v14 offset:0x1000
	ds_read_b64_tr_b16 v[158:159], v14 offset:0x1800
	ds_read_b64_tr_b16 v[192:193], v14 offset:0x2000
	ds_read_b64_tr_b16 v[194:195], v14 offset:0x2800
	ds_read_b64_tr_b16 v[196:197], v14 offset:0x3000
	v_mfma_f32_32x32x16_bf16 v[96:111], v[2:5], v[148:151], v[96:111]
	ds_read_b64_tr_b16 v[198:199], v14 offset:0x3800
	s_waitcnt lgkmcnt(0)
	v_mfma_f32_32x32x16_bf16 v[96:111], v[144:147], v[148:151], v[96:111]
	v_mfma_f32_32x32x16_bf16 v[96:111], v[10:13], v[148:151], v[96:111]
	v_mfma_f32_32x32x16_bf16 v[80:95], v[6:9], v[152:155], v[80:95]
	v_max_f32_e32 v244, v161, v161
	v_max_f32_e32 v252, v160, v160
	ds_read_b64_tr_b16 v[148:149], v14 offset:0x200
	ds_read_b64_tr_b16 v[150:151], v14 offset:0xa00
	ds_read_b64_tr_b16 v[152:153], v14 offset:0x1200
	ds_read_b64_tr_b16 v[154:155], v14 offset:0x1a00
	v_mfma_f32_32x32x16_bf16 v[80:95], v[2:5], v[156:159], v[80:95]
	v_max_f32_e32 v244, v252, v244
	v_max_f32_e32 v252, v128, v129
	ds_read_b64_tr_b16 v[156:157], v14 offset:0x2200
	ds_read_b64_tr_b16 v[158:159], v14 offset:0x2a00
	v_mfma_f32_32x32x16_bf16 v[80:95], v[144:147], v[192:195], v[80:95]
	v_max3_f32 v244, v244, v162, v163
	ds_read_b64_tr_b16 v[192:193], v14 offset:0x3200
	ds_read_b64_tr_b16 v[194:195], v14 offset:0x3a00
	s_waitcnt lgkmcnt(0)
	v_mfma_f32_32x32x16_bf16 v[80:95], v[10:13], v[196:199], v[80:95]
	v_max3_f32 v252, v252, v130, v131
	v_mfma_f32_32x32x16_bf16 v[64:79], v[6:9], v[148:151], v[64:79]
	v_max3_f32 v244, v244, v164, v165
	ds_read_b64_tr_b16 v[148:149], v14 offset:0x400
	ds_read_b64_tr_b16 v[150:151], v14 offset:0xc00
	v_mfma_f32_32x32x16_bf16 v[64:79], v[2:5], v[152:155], v[64:79]
	v_max3_f32 v252, v252, v132, v133
	ds_read_b64_tr_b16 v[152:153], v14 offset:0x1400
	ds_read_b64_tr_b16 v[154:155], v14 offset:0x1c00
	v_mfma_f32_32x32x16_bf16 v[64:79], v[144:147], v[156:159], v[64:79]
	v_max3_f32 v244, v244, v166, v167
	ds_read_b64_tr_b16 v[156:157], v14 offset:0x2400
	ds_read_b64_tr_b16 v[158:159], v14 offset:0x2c00
	v_mfma_f32_32x32x16_bf16 v[64:79], v[10:13], v[192:195], v[64:79]
	v_max3_f32 v252, v252, v134, v135
	ds_read_b64_tr_b16 v[192:193], v14 offset:0x3400
	ds_read_b64_tr_b16 v[194:195], v14 offset:0x3c00
	s_waitcnt lgkmcnt(0)
	v_mfma_f32_32x32x16_bf16 v[48:63], v[6:9], v[148:151], v[48:63]
	v_max3_f32 v244, v244, v168, v169
	ds_read_b64_tr_b16 v[148:149], v14 offset:0x600
	ds_read_b64_tr_b16 v[150:151], v14 offset:0xe00
	v_mfma_f32_32x32x16_bf16 v[48:63], v[2:5], v[152:155], v[48:63]
	v_max3_f32 v252, v252, v136, v137
	ds_read_b64_tr_b16 v[152:153], v14 offset:0x1600
	ds_read_b64_tr_b16 v[154:155], v14 offset:0x1e00
	v_mfma_f32_32x32x16_bf16 v[48:63], v[144:147], v[156:159], v[48:63]
	v_max3_f32 v244, v244, v170, v171
	ds_read_b64_tr_b16 v[156:157], v14 offset:0x2600
	ds_read_b64_tr_b16 v[158:159], v14 offset:0x2e00
	v_mfma_f32_32x32x16_bf16 v[48:63], v[10:13], v[192:195], v[48:63]
	v_max3_f32 v252, v252, v138, v139
	ds_read_b64_tr_b16 v[192:193], v14 offset:0x3600
	ds_read_b64_tr_b16 v[194:195], v14 offset:0x3e00
	s_waitcnt lgkmcnt(0)
	v_mfma_f32_32x32x16_bf16 v[32:47], v[6:9], v[148:151], v[32:47]
	v_max3_f32 v244, v244, v172, v173
	s_and_b64 vcc, exec, s[0:1]
	v_mfma_f32_32x32x16_bf16 v[32:47], v[2:5], v[152:155], v[32:47]
	v_max3_f32 v252, v252, v140, v141
	v_mfma_f32_32x32x16_bf16 v[32:47], v[144:147], v[156:159], v[32:47]
	v_max3_f32 v244, v244, v174, v175
	v_mfma_f32_32x32x16_bf16 v[32:47], v[10:13], v[192:195], v[32:47]
	v_max3_f32 v252, v252, v142, v143
	s_cbranch_vccnz .LBB0_724

; template <int MODE, bool FIRST, bool FOLD>
; __device__ __forceinline__ bool partialSM(f32x16& p0, f32x16& p1, float& m_reg, float& alpha, int relbase, bool near, const float* lut, float cb) {
;     ...
;     float pmax = p0[0];
; #pragma unroll
;     for (int r = 1; r < 16; ++r) pmax = fmaxf(pmax, p0[r]);
; #pragma unroll
;     for (int r = 0; r < 16; ++r) pmax = fmaxf(pmax, p1[r]);
;     { auto rr = __builtin_amdgcn_permlane32_swap(__float_as_uint(pmax), __float_as_uint(pmax), false, false);
;       pmax = fmaxf(__uint_as_float(rr[0]), __uint_as_float(rr[1])); }
;     bool resc;
;     if (FIRST && MODE != 2) resc = true; else resc = __any(pmax > THR2);
; template <int NQ, int MODE> ...
;     ...
;     f32x16 cinit = f32x16{}; float cur_cb = 0.f; bool dirty = true;
.LBB0_726:
	v_max_f32_e32 v2, v161, v161
	v_max_f32_e32 v3, v160, v160
	v_max_f32_e32 v2, v3, v2
	v_max_f32_e32 v3, v128, v129
	v_max3_f32 v2, v2, v162, v163
	v_max3_f32 v3, v3, v130, v131
	v_max3_f32 v2, v2, v164, v165
	v_max3_f32 v3, v3, v132, v133
	v_max3_f32 v2, v2, v166, v167
	v_max3_f32 v3, v3, v134, v135
	v_max3_f32 v2, v2, v168, v169
	v_max3_f32 v3, v3, v136, v137
	v_max3_f32 v2, v2, v170, v171
	v_max3_f32 v3, v3, v138, v139
	v_max3_f32 v2, v2, v172, v173
	v_max3_f32 v3, v3, v140, v141
	v_max3_f32 v2, v2, v174, v175
	v_max3_f32 v3, v3, v142, v143
	v_max_f32_e32 v2, v2, v3
	s_branch .Lmy_join_1
.Lmy_far_1:
	v_max_f32_e32 v2, v244, v252
.Lmy_join_1:
	v_mov_b32_e32 v3, v2
	s_nop 1
	v_permlane32_swap_b32_e32 v2, v3
	v_max_f32_e32 v3, v2, v3
	v_cmp_lt_f32_e32 vcc, s51, v3
	s_cmp_lg_u64 vcc, 0
	s_cselect_b64 s[20:21], -1, 0
	v_mov_b32_e32 v2, 1.0
	s_cbranch_vccnz .LBB0_736

; template <bool RSM> __device__ __forceinline__ void pv_d0(f32x16* o, f32x16& lacc, int vb, bf16x8 pa0, bf16x8 pa1, bf16x8 pa2, bf16x8 pa3) {
;     if (RSM) {
;         const bf16x8 ones = {0x3F80, 0x3F80, 0x3F80, 0x3F80, 0x3F80, 0x3F80, 0x3F80, 0x3F80};
;         lacc = __builtin_amdgcn_mfma_f32_32x32x16_bf16(pa0, ones, lacc, 0, 0, 0);
;         lacc = __builtin_amdgcn_mfma_f32_32x32x16_bf16(pa1, ones, lacc, 0, 0, 0);
;         lacc = __builtin_amdgcn_mfma_f32_32x32x16_bf16(pa2, ones, lacc, 0, 0, 0);
;         lacc = __builtin_amdgcn_mfma_f32_32x32x16_bf16(pa3, ones, lacc, 0, 0, 0); }
;     pv_one<0>(o[0], vb, pa0, pa1, pa2, pa3); pv_one<1>(o[1], vb, pa0, pa1, pa2, pa3); pv_one<2>(o[2], vb, pa0, pa1, pa2, pa3); pv_one<3>(o[3], vb, pa0, pa1, pa2, pa3);
; }
; template <int MODE, bool FIRST, bool FOLD>
; __device__ __forceinline__ bool partialSM(f32x16& p0, f32x16& p1, float& m_reg, float& alpha, int relbase, bool near, const float* lut, float cb) {
;     ...
;     float pmax = p0[0];
; #pragma unroll
;     for (int r = 1; r < 16; ++r) pmax = fmaxf(pmax, p0[r]);
; #pragma unroll
;     for (int r = 0; r < 16; ++r) pmax = fmaxf(pmax, p1[r]);
.Lmy_r2d_0:
	s_mov_b32 s38, s36
	s_mov_b32 s39, s36
	s_mov_b32 s37, s36
	v_mov_b64_e32 v[134:135], s[38:39]
	v_mov_b64_e32 v[132:133], s[36:37]
	s_lshl_b32 s23, s35, 14
	v_add_u32_e32 v0, s23, v230
	v_mfma_f32_32x32x16_bf16 v[96:111], v[6:9], v[132:135], v[96:111]
	ds_read_b64_tr_b16 v[136:137], v0 offset:0
	ds_read_b64_tr_b16 v[138:139], v0 offset:0x800
	ds_read_b64_tr_b16 v[140:141], v0 offset:0x1000
	ds_read_b64_tr_b16 v[142:143], v0 offset:0x1800
	ds_read_b64_tr_b16 v[192:193], v0 offset:0x2000
	ds_read_b64_tr_b16 v[194:195], v0 offset:0x2800
	ds_read_b64_tr_b16 v[196:197], v0 offset:0x3000
	v_mfma_f32_32x32x16_bf16 v[96:111], v[2:5], v[132:135], v[96:111]
	ds_read_b64_tr_b16 v[198:199], v0 offset:0x3800
	s_waitcnt lgkmcnt(0)
	v_mfma_f32_32x32x16_bf16 v[96:111], v[128:131], v[132:135], v[96:111]
	v_mfma_f32_32x32x16_bf16 v[96:111], v[10:13], v[132:135], v[96:111]
	v_mfma_f32_32x32x16_bf16 v[80:95], v[6:9], v[136:139], v[80:95]
	v_max_f32_e32 v203, v161, v161
	v_max_f32_e32 v204, v160, v160
	ds_read_b64_tr_b16 v[132:133], v0 offset:0x200
	ds_read_b64_tr_b16 v[134:135], v0 offset:0xa00
	ds_read_b64_tr_b16 v[136:137], v0 offset:0x1200
	ds_read_b64_tr_b16 v[138:139], v0 offset:0x1a00
	v_mfma_f32_32x32x16_bf16 v[80:95], v[2:5], v[140:143], v[80:95]
	v_max_f32_e32 v203, v204, v203
	v_max_f32_e32 v204, v144, v145
	ds_read_b64_tr_b16 v[140:141], v0 offset:0x2200
	ds_read_b64_tr_b16 v[142:143], v0 offset:0x2a00
	v_mfma_f32_32x32x16_bf16 v[80:95], v[128:131], v[192:195], v[80:95]
	v_max3_f32 v203, v203, v162, v163
	ds_read_b64_tr_b16 v[192:193], v0 offset:0x3200
	ds_read_b64_tr_b16 v[194:195], v0 offset:0x3a00
	s_waitcnt lgkmcnt(0)
	v_mfma_f32_32x32x16_bf16 v[80:95], v[10:13], v[196:199], v[80:95]
	v_max3_f32 v204, v204, v146, v147
	v_mfma_f32_32x32x16_bf16 v[64:79], v[6:9], v[132:135], v[64:79]
	v_max3_f32 v203, v203, v164, v165
	ds_read_b64_tr_b16 v[132:133], v0 offset:0x400
	ds_read_b64_tr_b16 v[134:135], v0 offset:0xc00
	v_mfma_f32_32x32x16_bf16 v[64:79], v[2:5], v[136:139], v[64:79]
	v_max3_f32 v204, v204, v148, v149
	ds_read_b64_tr_b16 v[136:137], v0 offset:0x1400
	ds_read_b64_tr_b16 v[138:139], v0 offset:0x1c00
	v_mfma_f32_32x32x16_bf16 v[64:79], v[128:131], v[140:143], v[64:79]
	v_max3_f32 v203, v203, v166, v167
	ds_read_b64_tr_b16 v[140:141], v0 offset:0x2400
	ds_read_b64_tr_b16 v[142:143], v0 offset:0x2c00
	v_mfma_f32_32x32x16_bf16 v[64:79], v[10:13], v[192:195], v[64:79]
	v_max3_f32 v204, v204, v150, v151
	ds_read_b64_tr_b16 v[192:193], v0 offset:0x3400
	ds_read_b64_tr_b16 v[194:195], v0 offset:0x3c00
	s_waitcnt lgkmcnt(0)
	v_mfma_f32_32x32x16_bf16 v[48:63], v[6:9], v[132:135], v[48:63]
	v_max3_f32 v203, v203, v168, v169
	ds_read_b64_tr_b16 v[132:133], v0 offset:0x600
	ds_read_b64_tr_b16 v[134:135], v0 offset:0xe00
	v_mfma_f32_32x32x16_bf16 v[48:63], v[2:5], v[136:139], v[48:63]
	v_max3_f32 v204, v204, v152, v153
	ds_read_b64_tr_b16 v[136:137], v0 offset:0x1600
	ds_read_b64_tr_b16 v[138:139], v0 offset:0x1e00
	v_mfma_f32_32x32x16_bf16 v[48:63], v[128:131], v[140:143], v[48:63]
	v_max3_f32 v203, v203, v170, v171
	ds_read_b64_tr_b16 v[140:141], v0 offset:0x2600
	ds_read_b64_tr_b16 v[142:143], v0 offset:0x2e00
	v_mfma_f32_32x32x16_bf16 v[48:63], v[10:13], v[192:195], v[48:63]
	v_max3_f32 v204, v204, v154, v155
	ds_read_b64_tr_b16 v[192:193], v0 offset:0x3600
	ds_read_b64_tr_b16 v[194:195], v0 offset:0x3e00
	s_waitcnt lgkmcnt(0)
	v_mfma_f32_32x32x16_bf16 v[32:47], v[6:9], v[132:135], v[32:47]
	v_max3_f32 v203, v203, v172, v173
	s_and_b64 vcc, exec, s[0:1]
	v_mfma_f32_32x32x16_bf16 v[32:47], v[2:5], v[136:139], v[32:47]
	v_max3_f32 v204, v204, v156, v157
	v_mfma_f32_32x32x16_bf16 v[32:47], v[128:131], v[140:143], v[32:47]
	v_max3_f32 v203, v203, v174, v175
	v_mfma_f32_32x32x16_bf16 v[32:47], v[10:13], v[192:195], v[32:47]
	v_max3_f32 v204, v204, v158, v159
	global_load_lds_dwordx4 v[214:215], off
	v_lshl_add_u64 v[214:215], v[214:215], 0, s[74:75]
	s_mov_b32 m0, s20
	s_nop 0
	global_load_lds_dwordx4 v[212:213], off
	v_lshl_add_u64 v[212:213], v[212:213], 0, s[74:75]
	s_add_i32 m0, s20, 0x2000
	s_nop 0
	global_load_lds_dwordx4 v[216:217], off
	v_lshl_add_u64 v[216:217], v[216:217], 0, s[74:75]
	s_cbranch_vccnz .LBB0_709
	s_branch .Lmy_r2ft_0
.Lmy_r2d_1:
	s_mov_b32 s38, s36
	s_mov_b32 s39, s36
	s_mov_b32 s37, s36
	v_mov_b64_e32 v[150:151], s[38:39]
	v_mov_b64_e32 v[148:149], s[36:37]
	s_lshl_b32 s37, s35, 14
	v_add_u32_e32 v14, s37, v230
	v_mfma_f32_32x32x16_bf16 v[96:111], v[6:9], v[148:151], v[96:111]
	ds_read_b64_tr_b16 v[152:153], v14 offset:0
	ds_read_b64_tr_b16 v[154:155], v14 offset:0x800
	ds_read_b64_tr_b16 v[156:157], v14 offset:0x1000
	ds_read_b64_tr_b16 v[158:159], v14 offset:0x1800
	ds_read_b64_tr_b16 v[192:193], v14 offset:0x2000
	ds_read_b64_tr_b16 v[194:195], v14 offset:0x2800
	ds_read_b64_tr_b16 v[196:197], v14 offset:0x3000
	v_mfma_f32_32x32x16_bf16 v[96:111], v[2:5], v[148:151], v[96:111]
	ds_read_b64_tr_b16 v[198:199], v14 offset:0x3800
	s_waitcnt lgkmcnt(0)
	v_mfma_f32_32x32x16_bf16 v[96:111], v[144:147], v[148:151], v[96:111]
	v_mfma_f32_32x32x16_bf16 v[96:111], v[10:13], v[148:151], v[96:111]
	v_mfma_f32_32x32x16_bf16 v[80:95], v[6:9], v[152:155], v[80:95]
	v_max_f32_e32 v244, v161, v161
	v_max_f32_e32 v252, v160, v160
	ds_read_b64_tr_b16 v[148:149], v14 offset:0x200
	ds_read_b64_tr_b16 v[150:151], v14 offset:0xa00
	ds_read_b64_tr_b16 v[152:153], v14 offset:0x1200
	ds_read_b64_tr_b16 v[154:155], v14 offset:0x1a00
	v_mfma_f32_32x32x16_bf16 v[80:95], v[2:5], v[156:159], v[80:95]
	v_max_f32_e32 v244, v252, v244
	v_max_f32_e32 v252, v128, v129
	ds_read_b64_tr_b16 v[156:157], v14 offset:0x2200
	ds_read_b64_tr_b16 v[158:159], v14 offset:0x2a00
	v_mfma_f32_32x32x16_bf16 v[80:95], v[144:147], v[192:195], v[80:95]
	v_max3_f32 v244, v244, v162, v163
	ds_read_b64_tr_b16 v[192:193], v14 offset:0x3200
	ds_read_b64_tr_b16 v[194:195], v14 offset:0x3a00
	s_waitcnt lgkmcnt(0)
; #define SBAR() __builtin_amdgcn_sched_barrier(0)
; template <int D0> __device__ __forceinline__ void pv_one(f32x16& od, int vb, bf16x8 pa0, bf16x8 pa1, bf16x8 pa2, bf16x8 pa3) {
;     const s16x4 l0 = tr_read<v_rd_off(D0, 0, 0)>(vb), h0 = tr_read<v_rd_off(D0, 0, 1)>(vb), l1 = tr_read<v_rd_off(D0, 1, 0)>(vb), h1 = tr_read<v_rd_off(D0, 1, 1)>(vb);
;     const s16x4 l2 = tr_read<v_rd_off(D0, 2, 0)>(vb), h2 = tr_read<v_rd_off(D0, 2, 1)>(vb), l3 = tr_read<v_rd_off(D0, 3, 0)>(vb), h3 = tr_read<v_rd_off(D0, 3, 1)>(vb);
;     asm volatile("s_waitcnt lgkmcnt(0)" ::: "memory"); SBAR();
;     ...
;     od = __builtin_amdgcn_mfma_f32_32x32x16_bf16(pa0, PK(l0, h0), od, 0, 0, 0);
;     od = __builtin_amdgcn_mfma_f32_32x32x16_bf16(pa1, PK(l1, h1), od, 0, 0, 0);
;     od = __builtin_amdgcn_mfma_f32_32x32x16_bf16(pa2, PK(l2, h2), od, 0, 0, 0);
;     od = __builtin_amdgcn_mfma_f32_32x32x16_bf16(pa3, PK(l3, h3), od, 0, 0, 0);
;     ...
; }
; template <bool RSM> __device__ __forceinline__ void pv_d0(f32x16* o, f32x16& lacc, int vb, bf16x8 pa0, bf16x8 pa1, bf16x8 pa2, bf16x8 pa3) {
;     if (RSM) {
;         const bf16x8 ones = {0x3F80, 0x3F80, 0x3F80, 0x3F80, 0x3F80, 0x3F80, 0x3F80, 0x3F80};
;         lacc = __builtin_amdgcn_mfma_f32_32x32x16_bf16(pa0, ones, lacc, 0, 0, 0);
;         lacc = __builtin_amdgcn_mfma_f32_32x32x16_bf16(pa1, ones, lacc, 0, 0, 0);
;         lacc = __builtin_amdgcn_mfma_f32_32x32x16_bf16(pa2, ones, lacc, 0, 0, 0);
;         lacc = __builtin_amdgcn_mfma_f32_32x32x16_bf16(pa3, ones, lacc, 0, 0, 0); }
;     pv_one<0>(o[0], vb, pa0, pa1, pa2, pa3); pv_one<1>(o[1], vb, pa0, pa1, pa2, pa3); pv_one<2>(o[2], vb, pa0, pa1, pa2, pa3); pv_one<3>(o[3], vb, pa0, pa1, pa2, pa3);
; }
; template <int MODE, bool FIRST, bool FOLD>
; __device__ __forceinline__ bool partialSM(f32x16& p0, f32x16& p1, float& m_reg, float& alpha, int relbase, bool near, const float* lut, float cb) {
;     ...
;     float pmax = p0[0];
; #pragma unroll
;     for (int r = 1; r < 16; ++r) pmax = fmaxf(pmax, p0[r]);
; #pragma unroll
;     for (int r = 0; r < 16; ++r) pmax = fmaxf(pmax, p1[r]);
	v_mfma_f32_32x32x16_bf16 v[80:95], v[10:13], v[196:199], v[80:95]
	v_max3_f32 v252, v252, v130, v131
	v_mfma_f32_32x32x16_bf16 v[64:79], v[6:9], v[148:151], v[64:79]
	v_max3_f32 v244, v244, v164, v165
	ds_read_b64_tr_b16 v[148:149], v14 offset:0x400
	ds_read_b64_tr_b16 v[150:151], v14 offset:0xc00
	v_mfma_f32_32x32x16_bf16 v[64:79], v[2:5], v[152:155], v[64:79]
	v_max3_f32 v252, v252, v132, v133
	ds_read_b64_tr_b16 v[152:153], v14 offset:0x1400
	ds_read_b64_tr_b16 v[154:155], v14 offset:0x1c00
	v_mfma_f32_32x32x16_bf16 v[64:79], v[144:147], v[156:159], v[64:79]
	v_max3_f32 v244, v244, v166, v167
	ds_read_b64_tr_b16 v[156:157], v14 offset:0x2400
	ds_read_b64_tr_b16 v[158:159], v14 offset:0x2c00
	v_mfma_f32_32x32x16_bf16 v[64:79], v[10:13], v[192:195], v[64:79]
	v_max3_f32 v252, v252, v134, v135
	ds_read_b64_tr_b16 v[192:193], v14 offset:0x3400
	ds_read_b64_tr_b16 v[194:195], v14 offset:0x3c00
	s_waitcnt lgkmcnt(0)
	v_mfma_f32_32x32x16_bf16 v[48:63], v[6:9], v[148:151], v[48:63]
	v_max3_f32 v244, v244, v168, v169
	ds_read_b64_tr_b16 v[148:149], v14 offset:0x600
	ds_read_b64_tr_b16 v[150:151], v14 offset:0xe00
	v_mfma_f32_32x32x16_bf16 v[48:63], v[2:5], v[152:155], v[48:63]
	v_max3_f32 v252, v252, v136, v137
	ds_read_b64_tr_b16 v[152:153], v14 offset:0x1600
	ds_read_b64_tr_b16 v[154:155], v14 offset:0x1e00
	v_mfma_f32_32x32x16_bf16 v[48:63], v[144:147], v[156:159], v[48:63]
	v_max3_f32 v244, v244, v170, v171
	ds_read_b64_tr_b16 v[156:157], v14 offset:0x2600
	ds_read_b64_tr_b16 v[158:159], v14 offset:0x2e00
	v_mfma_f32_32x32x16_bf16 v[48:63], v[10:13], v[192:195], v[48:63]
	v_max3_f32 v252, v252, v138, v139
	ds_read_b64_tr_b16 v[192:193], v14 offset:0x3600
	ds_read_b64_tr_b16 v[194:195], v14 offset:0x3e00
	s_waitcnt lgkmcnt(0)
	v_mfma_f32_32x32x16_bf16 v[32:47], v[6:9], v[148:151], v[32:47]
	v_max3_f32 v244, v244, v172, v173
	s_and_b64 vcc, exec, s[0:1]
	v_mfma_f32_32x32x16_bf16 v[32:47], v[2:5], v[152:155], v[32:47]
	v_max3_f32 v252, v252, v140, v141
	v_mfma_f32_32x32x16_bf16 v[32:47], v[144:147], v[156:159], v[32:47]
	v_max3_f32 v244, v244, v174, v175
	v_mfma_f32_32x32x16_bf16 v[32:47], v[10:13], v[192:195], v[32:47]
	v_max3_f32 v252, v252, v142, v143
	global_load_lds_dwordx4 v[214:215], off
	v_lshl_add_u64 v[214:215], v[214:215], 0, s[74:75]
	s_mov_b32 m0, s22
	s_nop 0
	global_load_lds_dwordx4 v[212:213], off
	v_lshl_add_u64 v[212:213], v[212:213], 0, s[74:75]
	s_add_i32 m0, s22, 0x2000
	s_nop 0
	global_load_lds_dwordx4 v[216:217], off
	v_lshl_add_u64 v[216:217], v[216:217], 0, s[74:75]
	s_cbranch_vccnz .LBB0_724
	s_branch .Lmy_r2ft_1
.Lmy_r2d_2:
	s_mov_b32 s38, s36
	s_mov_b32 s39, s36
	s_mov_b32 s37, s36
	v_mov_b64_e32 v[118:119], s[38:39]
	v_mov_b64_e32 v[116:117], s[36:37]
	s_lshl_b32 s15, s18, 14
	v_add_u32_e32 v0, s15, v192
	v_mfma_f32_32x32x16_bf16 v[80:95], v[6:9], v[116:119], v[80:95]
	ds_read_b64_tr_b16 v[120:121], v0 offset:0
	ds_read_b64_tr_b16 v[122:123], v0 offset:0x800
	ds_read_b64_tr_b16 v[124:125], v0 offset:0x1000
	ds_read_b64_tr_b16 v[126:127], v0 offset:0x1800
	ds_read_b64_tr_b16 v[176:177], v0 offset:0x2000
	ds_read_b64_tr_b16 v[178:179], v0 offset:0x2800
	ds_read_b64_tr_b16 v[180:181], v0 offset:0x3000
	v_mfma_f32_32x32x16_bf16 v[80:95], v[2:5], v[116:119], v[80:95]
	ds_read_b64_tr_b16 v[182:183], v0 offset:0x3800
	s_waitcnt lgkmcnt(0)
	v_mfma_f32_32x32x16_bf16 v[80:95], v[112:115], v[116:119], v[80:95]
	v_mfma_f32_32x32x16_bf16 v[80:95], v[10:13], v[116:119], v[80:95]
	v_mfma_f32_32x32x16_bf16 v[64:79], v[6:9], v[120:123], v[64:79]
	v_max_f32_e32 v203, v145, v145
	v_max_f32_e32 v204, v144, v144
	ds_read_b64_tr_b16 v[116:117], v0 offset:0x200
	ds_read_b64_tr_b16 v[118:119], v0 offset:0xa00
	ds_read_b64_tr_b16 v[120:121], v0 offset:0x1200
	ds_read_b64_tr_b16 v[122:123], v0 offset:0x1a00
	v_mfma_f32_32x32x16_bf16 v[64:79], v[2:5], v[124:127], v[64:79]
	v_max_f32_e32 v203, v204, v203
	v_max_f32_e32 v204, v128, v129
	ds_read_b64_tr_b16 v[124:125], v0 offset:0x2200
	ds_read_b64_tr_b16 v[126:127], v0 offset:0x2a00
	v_mfma_f32_32x32x16_bf16 v[64:79], v[112:115], v[176:179], v[64:79]
	v_max3_f32 v203, v203, v146, v147
	ds_read_b64_tr_b16 v[176:177], v0 offset:0x3200
	ds_read_b64_tr_b16 v[178:179], v0 offset:0x3a00
	s_waitcnt lgkmcnt(0)
	v_mfma_f32_32x32x16_bf16 v[64:79], v[10:13], v[180:183], v[64:79]
	v_max3_f32 v204, v204, v130, v131
	v_mfma_f32_32x32x16_bf16 v[48:63], v[6:9], v[116:119], v[48:63]
	v_max3_f32 v203, v203, v148, v149
	ds_read_b64_tr_b16 v[116:117], v0 offset:0x400
	ds_read_b64_tr_b16 v[118:119], v0 offset:0xc00
	v_mfma_f32_32x32x16_bf16 v[48:63], v[2:5], v[120:123], v[48:63]
	v_max3_f32 v204, v204, v132, v133
	ds_read_b64_tr_b16 v[120:121], v0 offset:0x1400
	ds_read_b64_tr_b16 v[122:123], v0 offset:0x1c00
	v_mfma_f32_32x32x16_bf16 v[48:63], v[112:115], v[124:127], v[48:63]
	v_max3_f32 v203, v203, v150, v151
	ds_read_b64_tr_b16 v[124:125], v0 offset:0x2400
	ds_read_b64_tr_b16 v[126:127], v0 offset:0x2c00
	v_mfma_f32_32x32x16_bf16 v[48:63], v[10:13], v[176:179], v[48:63]
	v_max3_f32 v204, v204, v134, v135
	ds_read_b64_tr_b16 v[176:177], v0 offset:0x3400
	ds_read_b64_tr_b16 v[178:179], v0 offset:0x3c00
	s_waitcnt lgkmcnt(0)
	v_mfma_f32_32x32x16_bf16 v[32:47], v[6:9], v[116:119], v[32:47]
	v_max3_f32 v203, v203, v152, v153
	ds_read_b64_tr_b16 v[116:117], v0 offset:0x600
	ds_read_b64_tr_b16 v[118:119], v0 offset:0xe00
	v_mfma_f32_32x32x16_bf16 v[32:47], v[2:5], v[120:123], v[32:47]
	v_max3_f32 v204, v204, v136, v137
	ds_read_b64_tr_b16 v[120:121], v0 offset:0x1600
	ds_read_b64_tr_b16 v[122:123], v0 offset:0x1e00
	v_mfma_f32_32x32x16_bf16 v[32:47], v[112:115], v[124:127], v[32:47]
	v_max3_f32 v203, v203, v154, v155
	ds_read_b64_tr_b16 v[124:125], v0 offset:0x2600
	ds_read_b64_tr_b16 v[126:127], v0 offset:0x2e00
	v_mfma_f32_32x32x16_bf16 v[32:47], v[10:13], v[176:179], v[32:47]
	v_max3_f32 v204, v204, v138, v139
	ds_read_b64_tr_b16 v[176:177], v0 offset:0x3600
	ds_read_b64_tr_b16 v[178:179], v0 offset:0x3e00
	s_waitcnt lgkmcnt(0)
	v_mfma_f32_32x32x16_bf16 v[16:31], v[6:9], v[116:119], v[16:31]
	v_max3_f32 v203, v203, v156, v157
	s_and_b64 vcc, exec, s[0:1]
	v_mfma_f32_32x32x16_bf16 v[16:31], v[2:5], v[120:123], v[16:31]
	v_max3_f32 v204, v204, v140, v141
	v_mfma_f32_32x32x16_bf16 v[16:31], v[112:115], v[124:127], v[16:31]
	v_max3_f32 v203, v203, v158, v159
	v_mfma_f32_32x32x16_bf16 v[16:31], v[10:13], v[176:179], v[16:31]
	v_max3_f32 v204, v204, v142, v143
	global_load_lds_dwordx4 v[184:185], off
	v_lshl_add_u64 v[184:185], v[184:185], 0, s[74:75]
	s_mov_b32 m0, s12
	s_nop 0
	global_load_lds_dwordx4 v[186:187], off
	v_lshl_add_u64 v[186:187], v[186:187], 0, s[74:75]
	s_add_i32 m0, s12, 0x2000
	s_nop 0
	global_load_lds_dwordx4 v[188:189], off
	v_lshl_add_u64 v[188:189], v[188:189], 0, s[74:75]
	s_cbranch_vccnz .LBB0_784
	s_branch .Lmy_r2ft_2
; #define SBAR() __builtin_amdgcn_sched_barrier(0)
; template <int D0> __device__ __forceinline__ void pv_one(f32x16& od, int vb, bf16x8 pa0, bf16x8 pa1, bf16x8 pa2, bf16x8 pa3) {
;     const s16x4 l0 = tr_read<v_rd_off(D0, 0, 0)>(vb), h0 = tr_read<v_rd_off(D0, 0, 1)>(vb), l1 = tr_read<v_rd_off(D0, 1, 0)>(vb), h1 = tr_read<v_rd_off(D0, 1, 1)>(vb);
;     const s16x4 l2 = tr_read<v_rd_off(D0, 2, 0)>(vb), h2 = tr_read<v_rd_off(D0, 2, 1)>(vb), l3 = tr_read<v_rd_off(D0, 3, 0)>(vb), h3 = tr_read<v_rd_off(D0, 3, 1)>(vb);
;     asm volatile("s_waitcnt lgkmcnt(0)" ::: "memory"); SBAR();
;     ...
;     od = __builtin_amdgcn_mfma_f32_32x32x16_bf16(pa0, PK(l0, h0), od, 0, 0, 0);
;     od = __builtin_amdgcn_mfma_f32_32x32x16_bf16(pa1, PK(l1, h1), od, 0, 0, 0);
;     od = __builtin_amdgcn_mfma_f32_32x32x16_bf16(pa2, PK(l2, h2), od, 0, 0, 0);
;     od = __builtin_amdgcn_mfma_f32_32x32x16_bf16(pa3, PK(l3, h3), od, 0, 0, 0);
;     ...
; }
; template <bool RSM> __device__ __forceinline__ void pv_d0(f32x16* o, f32x16& lacc, int vb, bf16x8 pa0, bf16x8 pa1, bf16x8 pa2, bf16x8 pa3) {
;     if (RSM) {
;         const bf16x8 ones = {0x3F80, 0x3F80, 0x3F80, 0x3F80, 0x3F80, 0x3F80, 0x3F80, 0x3F80};
;         lacc = __builtin_amdgcn_mfma_f32_32x32x16_bf16(pa0, ones, lacc, 0, 0, 0);
;         lacc = __builtin_amdgcn_mfma_f32_32x32x16_bf16(pa1, ones, lacc, 0, 0, 0);
;         lacc = __builtin_amdgcn_mfma_f32_32x32x16_bf16(pa2, ones, lacc, 0, 0, 0);
;         lacc = __builtin_amdgcn_mfma_f32_32x32x16_bf16(pa3, ones, lacc, 0, 0, 0); }
;     pv_one<0>(o[0], vb, pa0, pa1, pa2, pa3); pv_one<1>(o[1], vb, pa0, pa1, pa2, pa3); pv_one<2>(o[2], vb, pa0, pa1, pa2, pa3); pv_one<3>(o[3], vb, pa0, pa1, pa2, pa3);
; }
; template <int MODE, bool FIRST, bool FOLD>
; __device__ __forceinline__ bool partialSM(f32x16& p0, f32x16& p1, float& m_reg, float& alpha, int relbase, bool near, const float* lut, float cb) {
;     ...
;     float pmax = p0[0];
; #pragma unroll
;     for (int r = 1; r < 16; ++r) pmax = fmaxf(pmax, p0[r]);
; #pragma unroll
;     for (int r = 0; r < 16; ++r) pmax = fmaxf(pmax, p1[r]);
.Lmy_r2d_3:
	s_mov_b32 s38, s36
	s_mov_b32 s39, s36
	s_mov_b32 s37, s36
	v_mov_b64_e32 v[134:135], s[38:39]
	v_mov_b64_e32 v[132:133], s[36:37]
	s_lshl_b32 s31, s18, 14
	v_add_u32_e32 v14, s31, v192
	v_mfma_f32_32x32x16_bf16 v[80:95], v[6:9], v[132:135], v[80:95]
	ds_read_b64_tr_b16 v[136:137], v14 offset:0
	ds_read_b64_tr_b16 v[138:139], v14 offset:0x800
	ds_read_b64_tr_b16 v[140:141], v14 offset:0x1000
	ds_read_b64_tr_b16 v[142:143], v14 offset:0x1800
	ds_read_b64_tr_b16 v[176:177], v14 offset:0x2000
	ds_read_b64_tr_b16 v[178:179], v14 offset:0x2800
	ds_read_b64_tr_b16 v[180:181], v14 offset:0x3000
	v_mfma_f32_32x32x16_bf16 v[80:95], v[2:5], v[132:135], v[80:95]
	ds_read_b64_tr_b16 v[182:183], v14 offset:0x3800
	s_waitcnt lgkmcnt(0)
	v_mfma_f32_32x32x16_bf16 v[80:95], v[128:131], v[132:135], v[80:95]
	v_mfma_f32_32x32x16_bf16 v[80:95], v[10:13], v[132:135], v[80:95]
	v_mfma_f32_32x32x16_bf16 v[64:79], v[6:9], v[136:139], v[64:79]
	v_max_f32_e32 v225, v145, v145
	v_max_f32_e32 v230, v144, v144
	ds_read_b64_tr_b16 v[132:133], v14 offset:0x200
	ds_read_b64_tr_b16 v[134:135], v14 offset:0xa00
	ds_read_b64_tr_b16 v[136:137], v14 offset:0x1200
	ds_read_b64_tr_b16 v[138:139], v14 offset:0x1a00
	v_mfma_f32_32x32x16_bf16 v[64:79], v[2:5], v[140:143], v[64:79]
	v_max_f32_e32 v225, v230, v225
	v_max_f32_e32 v230, v112, v113
	ds_read_b64_tr_b16 v[140:141], v14 offset:0x2200
	ds_read_b64_tr_b16 v[142:143], v14 offset:0x2a00
	v_mfma_f32_32x32x16_bf16 v[64:79], v[128:131], v[176:179], v[64:79]
	v_max3_f32 v225, v225, v146, v147
	ds_read_b64_tr_b16 v[176:177], v14 offset:0x3200
	ds_read_b64_tr_b16 v[178:179], v14 offset:0x3a00
	s_waitcnt lgkmcnt(0)
	v_mfma_f32_32x32x16_bf16 v[64:79], v[10:13], v[180:183], v[64:79]
	v_max3_f32 v230, v230, v114, v115
	v_mfma_f32_32x32x16_bf16 v[48:63], v[6:9], v[132:135], v[48:63]
	v_max3_f32 v225, v225, v148, v149
	ds_read_b64_tr_b16 v[132:133], v14 offset:0x400
	ds_read_b64_tr_b16 v[134:135], v14 offset:0xc00
	v_mfma_f32_32x32x16_bf16 v[48:63], v[2:5], v[136:139], v[48:63]
	v_max3_f32 v230, v230, v116, v117
	ds_read_b64_tr_b16 v[136:137], v14 offset:0x1400
	ds_read_b64_tr_b16 v[138:139], v14 offset:0x1c00
	v_mfma_f32_32x32x16_bf16 v[48:63], v[128:131], v[140:143], v[48:63]
	v_max3_f32 v225, v225, v150, v151
	ds_read_b64_tr_b16 v[140:141], v14 offset:0x2400
	ds_read_b64_tr_b16 v[142:143], v14 offset:0x2c00
	v_mfma_f32_32x32x16_bf16 v[48:63], v[10:13], v[176:179], v[48:63]
	v_max3_f32 v230, v230, v118, v119
	ds_read_b64_tr_b16 v[176:177], v14 offset:0x3400
	ds_read_b64_tr_b16 v[178:179], v14 offset:0x3c00
	s_waitcnt lgkmcnt(0)
	v_mfma_f32_32x32x16_bf16 v[32:47], v[6:9], v[132:135], v[32:47]
	v_max3_f32 v225, v225, v152, v153
	ds_read_b64_tr_b16 v[132:133], v14 offset:0x600
	ds_read_b64_tr_b16 v[134:135], v14 offset:0xe00
	v_mfma_f32_32x32x16_bf16 v[32:47], v[2:5], v[136:139], v[32:47]
	v_max3_f32 v230, v230, v120, v121
	ds_read_b64_tr_b16 v[136:137], v14 offset:0x1600
	ds_read_b64_tr_b16 v[138:139], v14 offset:0x1e00
	v_mfma_f32_32x32x16_bf16 v[32:47], v[128:131], v[140:143], v[32:47]
	v_max3_f32 v225, v225, v154, v155
	ds_read_b64_tr_b16 v[140:141], v14 offset:0x2600
	ds_read_b64_tr_b16 v[142:143], v14 offset:0x2e00
	v_mfma_f32_32x32x16_bf16 v[32:47], v[10:13], v[176:179], v[32:47]
	v_max3_f32 v230, v230, v122, v123
	ds_read_b64_tr_b16 v[176:177], v14 offset:0x3600
	ds_read_b64_tr_b16 v[178:179], v14 offset:0x3e00
	s_waitcnt lgkmcnt(0)
	v_mfma_f32_32x32x16_bf16 v[16:31], v[6:9], v[132:135], v[16:31]
	v_max3_f32 v225, v225, v156, v157
	s_and_b64 vcc, exec, s[0:1]
	v_mfma_f32_32x32x16_bf16 v[16:31], v[2:5], v[136:139], v[16:31]
	v_max3_f32 v230, v230, v124, v125
	v_mfma_f32_32x32x16_bf16 v[16:31], v[128:131], v[140:143], v[16:31]
	v_max3_f32 v225, v225, v158, v159
	v_mfma_f32_32x32x16_bf16 v[16:31], v[10:13], v[176:179], v[16:31]
	v_max3_f32 v230, v230, v126, v127
	global_load_lds_dwordx4 v[184:185], off
	v_lshl_add_u64 v[184:185], v[184:185], 0, s[74:75]
	s_mov_b32 m0, s14
	s_nop 0
	global_load_lds_dwordx4 v[186:187], off
	v_lshl_add_u64 v[186:187], v[186:187], 0, s[74:75]
	s_add_i32 m0, s14, 0x2000
	s_nop 0
	global_load_lds_dwordx4 v[188:189], off
	v_lshl_add_u64 v[188:189], v[188:189], 0, s[74:75]
	s_cbranch_vccnz .LBB0_799
	s_branch .Lmy_r2ft_3

; #define SBAR() __builtin_amdgcn_sched_barrier(0)
; template <int D0> __device__ __forceinline__ void pv_one(f32x16& od, int vb, bf16x8 pa0, bf16x8 pa1, bf16x8 pa2, bf16x8 pa3) {
;     const s16x4 l0 = tr_read<v_rd_off(D0, 0, 0)>(vb), h0 = tr_read<v_rd_off(D0, 0, 1)>(vb), l1 = tr_read<v_rd_off(D0, 1, 0)>(vb), h1 = tr_read<v_rd_off(D0, 1, 1)>(vb);
;     const s16x4 l2 = tr_read<v_rd_off(D0, 2, 0)>(vb), h2 = tr_read<v_rd_off(D0, 2, 1)>(vb), l3 = tr_read<v_rd_off(D0, 3, 0)>(vb), h3 = tr_read<v_rd_off(D0, 3, 1)>(vb);
;     asm volatile("s_waitcnt lgkmcnt(0)" ::: "memory"); SBAR();
;     ...
;     od = __builtin_amdgcn_mfma_f32_32x32x16_bf16(pa0, PK(l0, h0), od, 0, 0, 0);
;     od = __builtin_amdgcn_mfma_f32_32x32x16_bf16(pa1, PK(l1, h1), od, 0, 0, 0);
;     od = __builtin_amdgcn_mfma_f32_32x32x16_bf16(pa2, PK(l2, h2), od, 0, 0, 0);
;     od = __builtin_amdgcn_mfma_f32_32x32x16_bf16(pa3, PK(l3, h3), od, 0, 0, 0);
;     ...
; }
; template <bool RSM> __device__ __forceinline__ void pv_d0(f32x16* o, f32x16& lacc, int vb, bf16x8 pa0, bf16x8 pa1, bf16x8 pa2, bf16x8 pa3) {
;     if (RSM) {
;         const bf16x8 ones = {0x3F80, 0x3F80, 0x3F80, 0x3F80, 0x3F80, 0x3F80, 0x3F80, 0x3F80};
;         lacc = __builtin_amdgcn_mfma_f32_32x32x16_bf16(pa0, ones, lacc, 0, 0, 0);
;         lacc = __builtin_amdgcn_mfma_f32_32x32x16_bf16(pa1, ones, lacc, 0, 0, 0);
;         lacc = __builtin_amdgcn_mfma_f32_32x32x16_bf16(pa2, ones, lacc, 0, 0, 0);
;         lacc = __builtin_amdgcn_mfma_f32_32x32x16_bf16(pa3, ones, lacc, 0, 0, 0); }
;     pv_one<0>(o[0], vb, pa0, pa1, pa2, pa3); pv_one<1>(o[1], vb, pa0, pa1, pa2, pa3); pv_one<2>(o[2], vb, pa0, pa1, pa2, pa3); pv_one<3>(o[3], vb, pa0, pa1, pa2, pa3);
; }
; template <int MODE, bool FIRST, bool FOLD>
; __device__ __forceinline__ bool partialSM(f32x16& p0, f32x16& p1, float& m_reg, float& alpha, int relbase, bool near, const float* lut, float cb) {
;     ...
;     float pmax = p0[0];
; #pragma unroll
;     for (int r = 1; r < 16; ++r) pmax = fmaxf(pmax, p0[r]);
; #pragma unroll
;     for (int r = 0; r < 16; ++r) pmax = fmaxf(pmax, p1[r]);
.LBB0_779:
	s_mov_b32 s38, s36
	s_mov_b32 s39, s36
	s_mov_b32 s37, s36
	v_mov_b64_e32 v[118:119], s[38:39]
	v_mov_b64_e32 v[116:117], s[36:37]
	s_lshl_b32 s15, s18, 14
	v_add_u32_e32 v0, s15, v192
	v_mfma_f32_32x32x16_bf16 v[80:95], v[6:9], v[116:119], v[80:95]
	ds_read_b64_tr_b16 v[120:121], v0 offset:0
	ds_read_b64_tr_b16 v[122:123], v0 offset:0x800
	ds_read_b64_tr_b16 v[124:125], v0 offset:0x1000
	ds_read_b64_tr_b16 v[126:127], v0 offset:0x1800
	ds_read_b64_tr_b16 v[176:177], v0 offset:0x2000
	ds_read_b64_tr_b16 v[178:179], v0 offset:0x2800
	ds_read_b64_tr_b16 v[180:181], v0 offset:0x3000
	v_mfma_f32_32x32x16_bf16 v[80:95], v[2:5], v[116:119], v[80:95]
	ds_read_b64_tr_b16 v[182:183], v0 offset:0x3800
	s_waitcnt lgkmcnt(0)
	v_mfma_f32_32x32x16_bf16 v[80:95], v[112:115], v[116:119], v[80:95]
	v_mfma_f32_32x32x16_bf16 v[80:95], v[10:13], v[116:119], v[80:95]
	v_mfma_f32_32x32x16_bf16 v[64:79], v[6:9], v[120:123], v[64:79]
	v_max_f32_e32 v203, v145, v145
	v_max_f32_e32 v204, v144, v144
	ds_read_b64_tr_b16 v[116:117], v0 offset:0x200
	ds_read_b64_tr_b16 v[118:119], v0 offset:0xa00
	ds_read_b64_tr_b16 v[120:121], v0 offset:0x1200
	ds_read_b64_tr_b16 v[122:123], v0 offset:0x1a00
	v_mfma_f32_32x32x16_bf16 v[64:79], v[2:5], v[124:127], v[64:79]
	v_max_f32_e32 v203, v204, v203
	v_max_f32_e32 v204, v128, v129
	ds_read_b64_tr_b16 v[124:125], v0 offset:0x2200
	ds_read_b64_tr_b16 v[126:127], v0 offset:0x2a00
	v_mfma_f32_32x32x16_bf16 v[64:79], v[112:115], v[176:179], v[64:79]
	v_max3_f32 v203, v203, v146, v147
	ds_read_b64_tr_b16 v[176:177], v0 offset:0x3200
	ds_read_b64_tr_b16 v[178:179], v0 offset:0x3a00
	s_waitcnt lgkmcnt(0)
	v_mfma_f32_32x32x16_bf16 v[64:79], v[10:13], v[180:183], v[64:79]
	v_max3_f32 v204, v204, v130, v131
	v_mfma_f32_32x32x16_bf16 v[48:63], v[6:9], v[116:119], v[48:63]
	v_max3_f32 v203, v203, v148, v149
	ds_read_b64_tr_b16 v[116:117], v0 offset:0x400
	ds_read_b64_tr_b16 v[118:119], v0 offset:0xc00
	v_mfma_f32_32x32x16_bf16 v[48:63], v[2:5], v[120:123], v[48:63]
	v_max3_f32 v204, v204, v132, v133
	ds_read_b64_tr_b16 v[120:121], v0 offset:0x1400
	ds_read_b64_tr_b16 v[122:123], v0 offset:0x1c00
	v_mfma_f32_32x32x16_bf16 v[48:63], v[112:115], v[124:127], v[48:63]
	v_max3_f32 v203, v203, v150, v151
	ds_read_b64_tr_b16 v[124:125], v0 offset:0x2400
	ds_read_b64_tr_b16 v[126:127], v0 offset:0x2c00
	v_mfma_f32_32x32x16_bf16 v[48:63], v[10:13], v[176:179], v[48:63]
	v_max3_f32 v204, v204, v134, v135
	ds_read_b64_tr_b16 v[176:177], v0 offset:0x3400
	ds_read_b64_tr_b16 v[178:179], v0 offset:0x3c00
	s_waitcnt lgkmcnt(0)
	v_mfma_f32_32x32x16_bf16 v[32:47], v[6:9], v[116:119], v[32:47]
	v_max3_f32 v203, v203, v152, v153
	ds_read_b64_tr_b16 v[116:117], v0 offset:0x600
	ds_read_b64_tr_b16 v[118:119], v0 offset:0xe00
	v_mfma_f32_32x32x16_bf16 v[32:47], v[2:5], v[120:123], v[32:47]
	v_max3_f32 v204, v204, v136, v137
	ds_read_b64_tr_b16 v[120:121], v0 offset:0x1600
	ds_read_b64_tr_b16 v[122:123], v0 offset:0x1e00
	v_mfma_f32_32x32x16_bf16 v[32:47], v[112:115], v[124:127], v[32:47]
	v_max3_f32 v203, v203, v154, v155
	ds_read_b64_tr_b16 v[124:125], v0 offset:0x2600
	ds_read_b64_tr_b16 v[126:127], v0 offset:0x2e00
	v_mfma_f32_32x32x16_bf16 v[32:47], v[10:13], v[176:179], v[32:47]
	v_max3_f32 v204, v204, v138, v139
	ds_read_b64_tr_b16 v[176:177], v0 offset:0x3600
	ds_read_b64_tr_b16 v[178:179], v0 offset:0x3e00
	s_waitcnt lgkmcnt(0)
	v_mfma_f32_32x32x16_bf16 v[16:31], v[6:9], v[116:119], v[16:31]
	v_max3_f32 v203, v203, v156, v157
	s_and_b64 vcc, exec, s[0:1]
	v_mfma_f32_32x32x16_bf16 v[16:31], v[2:5], v[120:123], v[16:31]
	v_max3_f32 v204, v204, v140, v141
	v_mfma_f32_32x32x16_bf16 v[16:31], v[112:115], v[124:127], v[16:31]
	v_max3_f32 v203, v203, v158, v159
	v_mfma_f32_32x32x16_bf16 v[16:31], v[10:13], v[176:179], v[16:31]
	v_max3_f32 v204, v204, v142, v143
	s_cbranch_vccnz .LBB0_784

; template <int MODE, bool FIRST, bool FOLD>
; __device__ __forceinline__ bool partialSM(f32x16& p0, f32x16& p1, float& m_reg, float& alpha, int relbase, bool near, const float* lut, float cb) {
;     ...
;     if (MODE != 0 && near) {
; #pragma unroll
;         for (int r = 0; r < 16; ++r) { const int rel = relbase + (r & 3) + 8 * (r >> 2), rel1 = rel + 32;
;             const int i0 = min(max(rel, -128), 128) + 128, i1 = min(max(rel1, -128), 128) + 128;
;             const float b0 = lut[i0], b1 = lut[i1];
;             if (MODE == 1) { p0[r] += b0; p1[r] += b1; }
;             else { p0[r] = (rel >= -128 && rel <= 128) ? p0[r] + b0 : -1e30f; p1[r] = (rel1 >= -128 && rel1 <= 128) ? p1[r] + b1 : -1e30f; } }
;     }
;     float pmax = p0[0];
; #pragma unroll
;     for (int r = 1; r < 16; ++r) pmax = fmaxf(pmax, p0[r]);
; #pragma unroll
;     for (int r = 0; r < 16; ++r) pmax = fmaxf(pmax, p1[r]);
.LBB0_786:
	v_max_f32_e32 v0, v145, v145
	v_max_f32_e32 v10, v144, v144
	v_max_f32_e32 v0, v10, v0
	v_max_f32_e32 v10, v128, v129
	v_max3_f32 v0, v0, v146, v147
	v_max3_f32 v10, v10, v130, v131
	v_max3_f32 v0, v0, v148, v149
	v_max3_f32 v10, v10, v132, v133
	v_max3_f32 v0, v0, v150, v151
	v_max3_f32 v10, v10, v134, v135
	v_max3_f32 v0, v0, v152, v153
	v_max3_f32 v10, v10, v136, v137
	v_max3_f32 v0, v0, v154, v155
	v_max3_f32 v10, v10, v138, v139
	v_max3_f32 v0, v0, v156, v157
	v_max3_f32 v10, v10, v140, v141
	v_max3_f32 v0, v0, v158, v159
	v_max3_f32 v10, v10, v142, v143
	v_max_f32_e32 v0, v0, v10
	s_branch .Lmy_join_2

; template <int MODE, bool FIRST, bool FOLD>
; __device__ __forceinline__ bool partialSM(f32x16& p0, f32x16& p1, float& m_reg, float& alpha, int relbase, bool near, const float* lut, float cb) {
;     ...
;     { auto rr = __builtin_amdgcn_permlane32_swap(__float_as_uint(pmax), __float_as_uint(pmax), false, false);
;       pmax = fmaxf(__uint_as_float(rr[0]), __uint_as_float(rr[1])); }
;     bool resc;
;     if (FIRST && MODE != 2) resc = true; else resc = __any(pmax > THR2);
;     if (__builtin_expect(resc, FIRST && MODE != 2)) {
;         const float delta = (FIRST && MODE != 2) ? pmax : fmaxf(pmax, 0.f);
;         m_reg += delta; alpha = (FIRST && MODE != 2) ? 1.f : __builtin_amdgcn_exp2f(-delta);
; #pragma unroll
;         for (int r = 0; r < 16; ++r) { p0[r] -= delta; p1[r] -= delta; }
;     } else alpha = 1.f;
.Lmy_join_2:
	v_mov_b32_e32 v10, v0
	s_nop 1
	v_permlane32_swap_b32_e32 v0, v10
	v_max_f32_e32 v10, v0, v10
	v_cmp_lt_f32_e32 vcc, s51, v10
	s_cmp_lg_u64 vcc, 0
	s_cselect_b64 s[14:15], -1, 0
	v_mov_b32_e32 v0, 1.0
	s_cbranch_vccnz .LBB0_806

; #define SBAR() __builtin_amdgcn_sched_barrier(0)
; template <int D0> __device__ __forceinline__ void pv_one(f32x16& od, int vb, bf16x8 pa0, bf16x8 pa1, bf16x8 pa2, bf16x8 pa3) {
;     const s16x4 l0 = tr_read<v_rd_off(D0, 0, 0)>(vb), h0 = tr_read<v_rd_off(D0, 0, 1)>(vb), l1 = tr_read<v_rd_off(D0, 1, 0)>(vb), h1 = tr_read<v_rd_off(D0, 1, 1)>(vb);
;     const s16x4 l2 = tr_read<v_rd_off(D0, 2, 0)>(vb), h2 = tr_read<v_rd_off(D0, 2, 1)>(vb), l3 = tr_read<v_rd_off(D0, 3, 0)>(vb), h3 = tr_read<v_rd_off(D0, 3, 1)>(vb);
;     asm volatile("s_waitcnt lgkmcnt(0)" ::: "memory"); SBAR();
;     ...
;     od = __builtin_amdgcn_mfma_f32_32x32x16_bf16(pa0, PK(l0, h0), od, 0, 0, 0);
;     od = __builtin_amdgcn_mfma_f32_32x32x16_bf16(pa1, PK(l1, h1), od, 0, 0, 0);
;     od = __builtin_amdgcn_mfma_f32_32x32x16_bf16(pa2, PK(l2, h2), od, 0, 0, 0);
;     od = __builtin_amdgcn_mfma_f32_32x32x16_bf16(pa3, PK(l3, h3), od, 0, 0, 0);
;     ...
; }
; template <bool RSM> __device__ __forceinline__ void pv_d0(f32x16* o, f32x16& lacc, int vb, bf16x8 pa0, bf16x8 pa1, bf16x8 pa2, bf16x8 pa3) {
;     if (RSM) {
;         const bf16x8 ones = {0x3F80, 0x3F80, 0x3F80, 0x3F80, 0x3F80, 0x3F80, 0x3F80, 0x3F80};
;         lacc = __builtin_amdgcn_mfma_f32_32x32x16_bf16(pa0, ones, lacc, 0, 0, 0);
;         lacc = __builtin_amdgcn_mfma_f32_32x32x16_bf16(pa1, ones, lacc, 0, 0, 0);
;         lacc = __builtin_amdgcn_mfma_f32_32x32x16_bf16(pa2, ones, lacc, 0, 0, 0);
;         lacc = __builtin_amdgcn_mfma_f32_32x32x16_bf16(pa3, ones, lacc, 0, 0, 0); }
;     pv_one<0>(o[0], vb, pa0, pa1, pa2, pa3); pv_one<1>(o[1], vb, pa0, pa1, pa2, pa3); pv_one<2>(o[2], vb, pa0, pa1, pa2, pa3); pv_one<3>(o[3], vb, pa0, pa1, pa2, pa3);
; }
; template <int MODE, bool FIRST, bool FOLD>
; __device__ __forceinline__ bool partialSM(f32x16& p0, f32x16& p1, float& m_reg, float& alpha, int relbase, bool near, const float* lut, float cb) {
;     ...
;     float pmax = p0[0];
; #pragma unroll
;     for (int r = 1; r < 16; ++r) pmax = fmaxf(pmax, p0[r]);
; #pragma unroll
;     for (int r = 0; r < 16; ++r) pmax = fmaxf(pmax, p1[r]);
.LBB0_794:
	s_mov_b32 s38, s36
	s_mov_b32 s39, s36
	s_mov_b32 s37, s36
	v_mov_b64_e32 v[134:135], s[38:39]
	v_mov_b64_e32 v[132:133], s[36:37]
	s_lshl_b32 s31, s18, 14
	v_add_u32_e32 v14, s31, v192
	v_mfma_f32_32x32x16_bf16 v[80:95], v[6:9], v[132:135], v[80:95]
	ds_read_b64_tr_b16 v[136:137], v14 offset:0
	ds_read_b64_tr_b16 v[138:139], v14 offset:0x800
	ds_read_b64_tr_b16 v[140:141], v14 offset:0x1000
	ds_read_b64_tr_b16 v[142:143], v14 offset:0x1800
	ds_read_b64_tr_b16 v[176:177], v14 offset:0x2000
	ds_read_b64_tr_b16 v[178:179], v14 offset:0x2800
	ds_read_b64_tr_b16 v[180:181], v14 offset:0x3000
	v_mfma_f32_32x32x16_bf16 v[80:95], v[2:5], v[132:135], v[80:95]
	ds_read_b64_tr_b16 v[182:183], v14 offset:0x3800
	s_waitcnt lgkmcnt(0)
	v_mfma_f32_32x32x16_bf16 v[80:95], v[128:131], v[132:135], v[80:95]
	v_mfma_f32_32x32x16_bf16 v[80:95], v[10:13], v[132:135], v[80:95]
	v_mfma_f32_32x32x16_bf16 v[64:79], v[6:9], v[136:139], v[64:79]
	v_max_f32_e32 v225, v145, v145
	v_max_f32_e32 v230, v144, v144
	ds_read_b64_tr_b16 v[132:133], v14 offset:0x200
	ds_read_b64_tr_b16 v[134:135], v14 offset:0xa00
	ds_read_b64_tr_b16 v[136:137], v14 offset:0x1200
	ds_read_b64_tr_b16 v[138:139], v14 offset:0x1a00
	v_mfma_f32_32x32x16_bf16 v[64:79], v[2:5], v[140:143], v[64:79]
	v_max_f32_e32 v225, v230, v225
	v_max_f32_e32 v230, v112, v113
	ds_read_b64_tr_b16 v[140:141], v14 offset:0x2200
	ds_read_b64_tr_b16 v[142:143], v14 offset:0x2a00
	v_mfma_f32_32x32x16_bf16 v[64:79], v[128:131], v[176:179], v[64:79]
	v_max3_f32 v225, v225, v146, v147
	ds_read_b64_tr_b16 v[176:177], v14 offset:0x3200
	ds_read_b64_tr_b16 v[178:179], v14 offset:0x3a00
	s_waitcnt lgkmcnt(0)
	v_mfma_f32_32x32x16_bf16 v[64:79], v[10:13], v[180:183], v[64:79]
	v_max3_f32 v230, v230, v114, v115
	v_mfma_f32_32x32x16_bf16 v[48:63], v[6:9], v[132:135], v[48:63]
	v_max3_f32 v225, v225, v148, v149
	ds_read_b64_tr_b16 v[132:133], v14 offset:0x400
	ds_read_b64_tr_b16 v[134:135], v14 offset:0xc00
	v_mfma_f32_32x32x16_bf16 v[48:63], v[2:5], v[136:139], v[48:63]
	v_max3_f32 v230, v230, v116, v117
	ds_read_b64_tr_b16 v[136:137], v14 offset:0x1400
	ds_read_b64_tr_b16 v[138:139], v14 offset:0x1c00
	v_mfma_f32_32x32x16_bf16 v[48:63], v[128:131], v[140:143], v[48:63]
	v_max3_f32 v225, v225, v150, v151
	ds_read_b64_tr_b16 v[140:141], v14 offset:0x2400
	ds_read_b64_tr_b16 v[142:143], v14 offset:0x2c00
	v_mfma_f32_32x32x16_bf16 v[48:63], v[10:13], v[176:179], v[48:63]
	v_max3_f32 v230, v230, v118, v119
	ds_read_b64_tr_b16 v[176:177], v14 offset:0x3400
	ds_read_b64_tr_b16 v[178:179], v14 offset:0x3c00
	s_waitcnt lgkmcnt(0)
	v_mfma_f32_32x32x16_bf16 v[32:47], v[6:9], v[132:135], v[32:47]
	v_max3_f32 v225, v225, v152, v153
	ds_read_b64_tr_b16 v[132:133], v14 offset:0x600
	ds_read_b64_tr_b16 v[134:135], v14 offset:0xe00
	v_mfma_f32_32x32x16_bf16 v[32:47], v[2:5], v[136:139], v[32:47]
	v_max3_f32 v230, v230, v120, v121
	ds_read_b64_tr_b16 v[136:137], v14 offset:0x1600
	ds_read_b64_tr_b16 v[138:139], v14 offset:0x1e00
	v_mfma_f32_32x32x16_bf16 v[32:47], v[128:131], v[140:143], v[32:47]
	v_max3_f32 v225, v225, v154, v155
	ds_read_b64_tr_b16 v[140:141], v14 offset:0x2600
	ds_read_b64_tr_b16 v[142:143], v14 offset:0x2e00
	v_mfma_f32_32x32x16_bf16 v[32:47], v[10:13], v[176:179], v[32:47]
	v_max3_f32 v230, v230, v122, v123
	ds_read_b64_tr_b16 v[176:177], v14 offset:0x3600
	ds_read_b64_tr_b16 v[178:179], v14 offset:0x3e00
	s_waitcnt lgkmcnt(0)
	v_mfma_f32_32x32x16_bf16 v[16:31], v[6:9], v[132:135], v[16:31]
	v_max3_f32 v225, v225, v156, v157
	s_and_b64 vcc, exec, s[0:1]
	v_mfma_f32_32x32x16_bf16 v[16:31], v[2:5], v[136:139], v[16:31]
	v_max3_f32 v230, v230, v124, v125
	v_mfma_f32_32x32x16_bf16 v[16:31], v[128:131], v[140:143], v[16:31]
	v_max3_f32 v225, v225, v158, v159
	v_mfma_f32_32x32x16_bf16 v[16:31], v[10:13], v[176:179], v[16:31]
	v_max3_f32 v230, v230, v126, v127
	s_cbranch_vccnz .LBB0_799

; template <int MODE, bool FIRST, bool FOLD>
; __device__ __forceinline__ bool partialSM(f32x16& p0, f32x16& p1, float& m_reg, float& alpha, int relbase, bool near, const float* lut, float cb) {
;     ...
;     if (MODE != 0 && near) {
; #pragma unroll
;         for (int r = 0; r < 16; ++r) { const int rel = relbase + (r & 3) + 8 * (r >> 2), rel1 = rel + 32;
;             const int i0 = min(max(rel, -128), 128) + 128, i1 = min(max(rel1, -128), 128) + 128;
;             const float b0 = lut[i0], b1 = lut[i1];
;             if (MODE == 1) { p0[r] += b0; p1[r] += b1; }
;             else { p0[r] = (rel >= -128 && rel <= 128) ? p0[r] + b0 : -1e30f; p1[r] = (rel1 >= -128 && rel1 <= 128) ? p1[r] + b1 : -1e30f; } }
;     }
;     float pmax = p0[0];
; #pragma unroll
;     for (int r = 1; r < 16; ++r) pmax = fmaxf(pmax, p0[r]);
; #pragma unroll
;     for (int r = 0; r < 16; ++r) pmax = fmaxf(pmax, p1[r]);
;     { auto rr = __builtin_amdgcn_permlane32_swap(__float_as_uint(pmax), __float_as_uint(pmax), false, false);
;       pmax = fmaxf(__uint_as_float(rr[0]), __uint_as_float(rr[1])); }
;     bool resc;
;     if (FIRST && MODE != 2) resc = true; else resc = __any(pmax > THR2);
;     if (__builtin_expect(resc, FIRST && MODE != 2)) {
;         const float delta = (FIRST && MODE != 2) ? pmax : fmaxf(pmax, 0.f);
;         m_reg += delta; alpha = (FIRST && MODE != 2) ? 1.f : __builtin_amdgcn_exp2f(-delta);
; #pragma unroll
;         for (int r = 0; r < 16; ++r) { p0[r] -= delta; p1[r] -= delta; }
;     } else alpha = 1.f;
.LBB0_801:
	v_max_f32_e32 v2, v145, v145
	v_max_f32_e32 v3, v144, v144
	v_max_f32_e32 v2, v3, v2
	v_max_f32_e32 v3, v112, v113
	v_max3_f32 v2, v2, v146, v147
	v_max3_f32 v3, v3, v114, v115
	v_max3_f32 v2, v2, v148, v149
	v_max3_f32 v3, v3, v116, v117
	v_max3_f32 v2, v2, v150, v151
	v_max3_f32 v3, v3, v118, v119
	v_max3_f32 v2, v2, v152, v153
	v_max3_f32 v3, v3, v120, v121
	v_max3_f32 v2, v2, v154, v155
	v_max3_f32 v3, v3, v122, v123
	v_max3_f32 v2, v2, v156, v157
	v_max3_f32 v3, v3, v124, v125
	v_max3_f32 v2, v2, v158, v159
	v_max3_f32 v3, v3, v126, v127
	v_max_f32_e32 v2, v2, v3
	s_branch .Lmy_join_3
.Lmy_far_3:
	v_max_f32_e32 v2, v225, v230
.Lmy_join_3:
	v_mov_b32_e32 v3, v2
	s_nop 1
	v_permlane32_swap_b32_e32 v2, v3
	v_max_f32_e32 v3, v2, v3
	v_cmp_lt_f32_e32 vcc, s51, v3
	s_cmp_lg_u64 vcc, 0
	s_cselect_b64 s[12:13], -1, 0
	v_mov_b32_e32 v2, 1.0
	s_cbranch_vccnz .LBB0_811
